# scan producers: wave 7 finalize packs bf16 with v_cvt_pk_bf16_f32 instead of the 6-op integer RNE trick; stats on wave 5
# speedup vs baseline: 1.0017x; 1.0009x over previous
.LBB0_988:
	s_or_b64 exec, exec, s[14:15]
	s_and_b32 s14, s16, 3
	s_waitcnt lgkmcnt(0)
	v_lshlrev_b32_e32 v84, 2, v117
	v_lshl_or_b32 v84, s14, 12, v84
	v_add_u32_e32 v84, 0, v84
	v_lshl_add_u32 v194, s14, 8, v173
	v_add_u32_e32 v206, 0x15400, v84
	v_add_u32_e32 v210, 0x19400, v84
	v_add_u32_e32 v222, 0x1d400, v84
	ds_read_b64 v[226:227], v172
	ds_read_b128 v[84:87], v171
	ds_read_b128 v[88:91], v171 offset:16
	ds_read_b128 v[92:95], v171 offset:32
	ds_read_b128 v[96:99], v171 offset:48
	ds_read_b128 v[100:103], v169
	ds_read_b128 v[104:107], v169 offset:16
	ds_read_b128 v[108:111], v169 offset:32
	ds_read_b128 v[158:161], v206
	ds_read_b64 v[214:215], v194
	ds_read_b128 v[194:197], v169 offset:48
	ds_read_b128 v[198:201], v206 offset:16
	ds_read_b128 v[202:205], v206 offset:32
	ds_read_b128 v[206:209], v206 offset:48
	s_waitcnt lgkmcnt(5)
	v_sub_f32_e32 v159, v159, v226
	v_sub_f32_e32 v158, v158, v226
	v_sub_f32_e32 v161, v161, v226
	v_sub_f32_e32 v160, v160, v226
	v_pk_mul_f32 v[160:161], v[226:227], v[160:161] op_sel:[1,0]
	v_pk_mul_f32 v[158:159], v[226:227], v[158:159] op_sel:[1,0]
	v_pk_fma_f32 v[216:217], v[86:87], v[160:161], v[102:103]
	v_pk_fma_f32 v[218:219], v[84:85], v[158:159], v[100:101]
	ds_read_b128 v[84:87], v210
	ds_read_b128 v[100:103], v210 offset:16
	ds_read_b128 v[158:161], v210 offset:32
	ds_read_b128 v[210:213], v210 offset:48
	s_waitcnt lgkmcnt(8)
	v_add_f32_e32 v228, v214, v215
	s_waitcnt lgkmcnt(3)
	v_pk_fma_f32 v[230:231], v[228:229], v[86:87], v[216:217] op_sel_hi:[0,1,1]
	ds_read_b128 v[214:217], v222
	v_pk_fma_f32 v[232:233], v[228:229], v[84:85], v[218:219] op_sel_hi:[0,1,1]
	v_sub_f32_e32 v199, v199, v226
	v_sub_f32_e32 v198, v198, v226
	ds_read_b128 v[84:87], v222 offset:16
	ds_read_b128 v[218:221], v222 offset:32
	ds_read_b128 v[222:225], v222 offset:48
	s_waitcnt lgkmcnt(3)
	v_pk_mul_f32 v[214:215], v[214:215], v[232:233]
	v_pk_mul_f32 v[198:199], v[226:227], v[198:199] op_sel:[1,0]
	v_pk_fma_f32 v[88:89], v[88:89], v[198:199], v[104:105]
	v_sub_f32_e32 v201, v201, v226
	v_sub_f32_e32 v200, v200, v226
	v_pk_fma_f32 v[88:89], v[228:229], v[100:101], v[88:89] op_sel_hi:[0,1,1]
	v_pk_mul_f32 v[216:217], v[216:217], v[230:231]
	v_pk_mul_f32 v[200:201], v[226:227], v[200:201] op_sel:[1,0]
	s_waitcnt lgkmcnt(2)
	v_pk_mul_f32 v[84:85], v[84:85], v[88:89]
	v_cvt_pk_bf16_f32 v214, v214, v215
	v_pk_fma_f32 v[90:91], v[90:91], v[200:201], v[106:107]
	v_pk_fma_f32 v[90:91], v[228:229], v[102:103], v[90:91] op_sel_hi:[0,1,1]
	v_pk_mul_f32 v[86:87], v[86:87], v[90:91]
	v_cvt_pk_bf16_f32 v215, v216, v217
	v_cvt_pk_bf16_f32 v216, v84, v85
	v_cvt_pk_bf16_f32 v217, v86, v87
	v_sub_f32_e32 v85, v203, v226
	v_sub_f32_e32 v84, v202, v226
	v_pk_mul_f32 v[84:85], v[226:227], v[84:85] op_sel:[1,0]
	v_sub_f32_e32 v87, v205, v226
	v_pk_fma_f32 v[84:85], v[92:93], v[84:85], v[108:109]
	v_sub_f32_e32 v86, v204, v226
	v_pk_fma_f32 v[84:85], v[228:229], v[158:159], v[84:85] op_sel_hi:[0,1,1]
	v_pk_mul_f32 v[86:87], v[226:227], v[86:87] op_sel:[1,0]
	s_waitcnt lgkmcnt(1)
	v_pk_mul_f32 v[84:85], v[218:219], v[84:85]
	v_pk_fma_f32 v[86:87], v[94:95], v[86:87], v[110:111]
	v_pk_fma_f32 v[86:87], v[228:229], v[160:161], v[86:87] op_sel_hi:[0,1,1]
	v_pk_mul_f32 v[86:87], v[220:221], v[86:87]
	v_cvt_pk_bf16_f32 v84, v84, v85
	v_cvt_pk_bf16_f32 v85, v86, v87
	v_sub_f32_e32 v87, v207, v226
	v_sub_f32_e32 v86, v206, v226
	v_pk_mul_f32 v[86:87], v[226:227], v[86:87] op_sel:[1,0]
	v_sub_f32_e32 v89, v209, v226
	v_pk_fma_f32 v[86:87], v[96:97], v[86:87], v[194:195]
	v_sub_f32_e32 v88, v208, v226
	v_pk_fma_f32 v[86:87], v[228:229], v[210:211], v[86:87] op_sel_hi:[0,1,1]
	v_pk_mul_f32 v[88:89], v[226:227], v[88:89] op_sel:[1,0]
	s_waitcnt lgkmcnt(0)
	v_pk_mul_f32 v[86:87], v[222:223], v[86:87]
	v_pk_fma_f32 v[88:89], v[98:99], v[88:89], v[196:197]
	v_pk_fma_f32 v[88:89], v[228:229], v[212:213], v[88:89] op_sel_hi:[0,1,1]
	v_pk_mul_f32 v[88:89], v[224:225], v[88:89]
	v_cvt_pk_bf16_f32 v86, v86, v87
	s_lshl_b32 s58, s16, 5
	v_cvt_pk_bf16_f32 v87, v88, v89
	v_lshl_add_u64 v[88:89], v[114:115], 0, s[58:59]
	v_lshlrev_b64 v[88:89], 12, v[88:89]
	v_lshl_add_u64 v[88:89], v[156:157], 0, v[88:89]
	s_waitcnt vmcnt(1)
	v_mov_b64_e32 v[158:159], v[82:83]
	s_waitcnt vmcnt(0)
	v_mov_b64_e32 v[160:161], v[80:81]
	global_store_dwordx4 v[88:89], v[214:217], off
	global_store_dwordx4 v[88:89], v[84:87], off offset:16

.LBB0_1012:
	s_or_b64 exec, exec, s[18:19]
	s_and_b32 s17, s16, 3
	s_waitcnt lgkmcnt(0)
	v_lshlrev_b32_e32 v84, 2, v117
	v_lshl_or_b32 v84, s17, 12, v84
	v_add_u32_e32 v84, 0, v84
	v_lshl_add_u32 v194, s17, 8, v173
	v_add_u32_e32 v206, 0x15400, v84
	v_add_u32_e32 v210, 0x19400, v84
	v_add_u32_e32 v222, 0x1d400, v84
	ds_read_b64 v[226:227], v172
	ds_read_b128 v[84:87], v171
	ds_read_b128 v[88:91], v171 offset:16
	ds_read_b128 v[92:95], v171 offset:32
	ds_read_b128 v[96:99], v171 offset:48
	ds_read_b128 v[100:103], v169
	ds_read_b128 v[104:107], v169 offset:16
	ds_read_b128 v[108:111], v169 offset:32
	ds_read_b128 v[158:161], v206
	ds_read_b64 v[214:215], v194
	ds_read_b128 v[194:197], v169 offset:48
	ds_read_b128 v[198:201], v206 offset:16
	ds_read_b128 v[202:205], v206 offset:32
	ds_read_b128 v[206:209], v206 offset:48
	s_waitcnt lgkmcnt(5)
	v_sub_f32_e32 v159, v159, v226
	v_sub_f32_e32 v158, v158, v226
	v_sub_f32_e32 v161, v161, v226
	v_sub_f32_e32 v160, v160, v226
	v_pk_mul_f32 v[160:161], v[226:227], v[160:161] op_sel:[1,0]
	v_pk_mul_f32 v[158:159], v[226:227], v[158:159] op_sel:[1,0]
	v_pk_fma_f32 v[216:217], v[86:87], v[160:161], v[102:103]
	v_pk_fma_f32 v[218:219], v[84:85], v[158:159], v[100:101]
	ds_read_b128 v[84:87], v210
	ds_read_b128 v[100:103], v210 offset:16
	ds_read_b128 v[158:161], v210 offset:32
	ds_read_b128 v[210:213], v210 offset:48
	s_waitcnt lgkmcnt(8)
	v_add_f32_e32 v228, v214, v215
	s_waitcnt lgkmcnt(3)
	v_pk_fma_f32 v[230:231], v[228:229], v[86:87], v[216:217] op_sel_hi:[0,1,1]
	ds_read_b128 v[214:217], v222
	v_pk_fma_f32 v[232:233], v[228:229], v[84:85], v[218:219] op_sel_hi:[0,1,1]
	v_sub_f32_e32 v199, v199, v226
	v_sub_f32_e32 v198, v198, v226
	ds_read_b128 v[84:87], v222 offset:16
	ds_read_b128 v[218:221], v222 offset:32
	ds_read_b128 v[222:225], v222 offset:48
	s_waitcnt lgkmcnt(3)
	v_pk_mul_f32 v[214:215], v[214:215], v[232:233]
	v_pk_mul_f32 v[198:199], v[226:227], v[198:199] op_sel:[1,0]
	v_pk_fma_f32 v[88:89], v[88:89], v[198:199], v[104:105]
	v_sub_f32_e32 v201, v201, v226
	v_sub_f32_e32 v200, v200, v226
	v_pk_fma_f32 v[88:89], v[228:229], v[100:101], v[88:89] op_sel_hi:[0,1,1]
	v_pk_mul_f32 v[216:217], v[216:217], v[230:231]
	v_pk_mul_f32 v[200:201], v[226:227], v[200:201] op_sel:[1,0]
	s_waitcnt lgkmcnt(2)
	v_pk_mul_f32 v[84:85], v[84:85], v[88:89]
	v_cvt_pk_bf16_f32 v214, v214, v215
	v_pk_fma_f32 v[90:91], v[90:91], v[200:201], v[106:107]
	v_pk_fma_f32 v[90:91], v[228:229], v[102:103], v[90:91] op_sel_hi:[0,1,1]
	v_pk_mul_f32 v[86:87], v[86:87], v[90:91]
	v_cvt_pk_bf16_f32 v215, v216, v217
	v_cvt_pk_bf16_f32 v216, v84, v85
	v_cvt_pk_bf16_f32 v217, v86, v87
	v_sub_f32_e32 v85, v203, v226
	v_sub_f32_e32 v84, v202, v226
	v_pk_mul_f32 v[84:85], v[226:227], v[84:85] op_sel:[1,0]
	v_sub_f32_e32 v87, v205, v226
	v_pk_fma_f32 v[84:85], v[92:93], v[84:85], v[108:109]
	v_sub_f32_e32 v86, v204, v226
	v_pk_fma_f32 v[84:85], v[228:229], v[158:159], v[84:85] op_sel_hi:[0,1,1]
	v_pk_mul_f32 v[86:87], v[226:227], v[86:87] op_sel:[1,0]
	s_waitcnt lgkmcnt(1)
	v_pk_mul_f32 v[84:85], v[218:219], v[84:85]
	v_pk_fma_f32 v[86:87], v[94:95], v[86:87], v[110:111]
	v_pk_fma_f32 v[86:87], v[228:229], v[160:161], v[86:87] op_sel_hi:[0,1,1]
	v_pk_mul_f32 v[86:87], v[220:221], v[86:87]
	v_cvt_pk_bf16_f32 v84, v84, v85
	v_cvt_pk_bf16_f32 v85, v86, v87
	v_sub_f32_e32 v87, v207, v226
	v_sub_f32_e32 v86, v206, v226
	v_pk_mul_f32 v[86:87], v[226:227], v[86:87] op_sel:[1,0]
	v_sub_f32_e32 v89, v209, v226
	v_pk_fma_f32 v[86:87], v[96:97], v[86:87], v[194:195]
	v_sub_f32_e32 v88, v208, v226
	v_pk_fma_f32 v[86:87], v[228:229], v[210:211], v[86:87] op_sel_hi:[0,1,1]
	v_pk_mul_f32 v[88:89], v[226:227], v[88:89] op_sel:[1,0]
	s_waitcnt lgkmcnt(0)
	v_pk_mul_f32 v[86:87], v[222:223], v[86:87]
	v_pk_fma_f32 v[88:89], v[98:99], v[88:89], v[196:197]
	v_pk_fma_f32 v[88:89], v[228:229], v[212:213], v[88:89] op_sel_hi:[0,1,1]
	v_pk_mul_f32 v[88:89], v[224:225], v[88:89]
	v_cvt_pk_bf16_f32 v86, v86, v87
	s_lshl_b32 s58, s16, 5
	v_cvt_pk_bf16_f32 v87, v88, v89
	v_lshl_add_u64 v[88:89], v[114:115], 0, s[58:59]
	v_lshlrev_b64 v[88:89], 12, v[88:89]
	v_lshl_add_u64 v[88:89], v[156:157], 0, v[88:89]
	s_waitcnt vmcnt(1)
	v_mov_b64_e32 v[158:159], v[82:83]
	s_waitcnt vmcnt(0)
	v_mov_b64_e32 v[160:161], v[80:81]
	global_store_dwordx4 v[88:89], v[214:217], off
	global_store_dwordx4 v[88:89], v[84:87], off offset:16
